# v30 + layer-0 PLE-proj weight conversion assigned to the waves with one fewer gate/up item (prologue balance)
# baseline (speedup 1.0000x reference)
; #define LAS __attribute__((address_space(3)))
; __device__ __forceinline__ void convert_range(unsigned char* lds, int lo, int hi, int w, int nworkers, int wave, int lane) {
;     const XItem* tab = (const XItem*)(lds + 8 * 16640);
;     LAS float* scr = (LAS float*)((LAS unsigned char*)lds + wave * 16640);
;     int it = lo + w; if (it >= hi) return;
;     f32x4 v[16]; float gv[16]; ItemPos p = item_load(tab, it, lane, v, gv);
; __global__ void __launch_bounds__(NTHREADS, 2) mega_fwd(KArgs a_unused) {
;     ...
;         if (((32 * 44) % G != 0) && ((32 * 18) % G != 0)) { convert_range(lds, 0, 5632, gw, NGW, wave, lane); convert_range(lds, 10752, 17408, gw, NGW, wave, lane); convert_range(lds, 21248, ITEMS_L, gw, NGW, wave, lane); convert_range(lds, ITEMS_L + 21248, 2 * ITEMS_L, gw, NGW, wave, lane); }
.LBB0_157:
	s_sub_i32 s23, s12, 0x600
	s_cmp_lt_u32 s23, 0x80
	s_cselect_b64 s[18:19], -1, 0
	s_cbranch_scc0 .LBB0_226
	s_add_i32 s23, s12, 0x4d00
	s_mov_b32 s0, s23
	s_mov_b32 s1, 2
	s_mov_b32 s2, 1
	s_mov_b32 s3, 0
	v_bfrev_b32_e32 v2, 1
	v_bfrev_b32_e32 v3, 1
